# nt hint on read-once f32 weight loads of the weight conversion and on the input loads of init (streaming data kept out of the cache hierarchy)
# speedup vs baseline: 1.0334x; 1.0016x over previous
; DI int opaque_tid() { int t = threadIdx.x; asm volatile("" : "+v"(t)); return t; }
; DI void init_h(const Params& p) {
;     ...
;   for (size_t i = (size_t)blockIdx.x * NT + opaque_tid(); i < n4; i += (size_t)gridDim.x * NT) {
;     const size_t e = i * 4;
;     const int row = (int)(e / D), col = (int)(e % D);
;     const int b = row / T, t = row % T;
;     f32x4 v = t < 16 ? *(const f32x4*)(p.meta + (size_t)t * D + col) : *(const f32x4*)(p.x + ((size_t)b * 2048 + (t - 16)) * D + col);
;     *(f32x4*)(h + e) = v;
;     *(u32x2*)(hb + e) = MK2(pack2(v[0], v[1]), pack2(v[2], v[3]));
;   }
.LBB0_7:
	s_or_b64 exec, exec, s[18:19]
	global_load_dwordx4 v[12:15], v[12:13], off nt
	v_lshl_add_u64 v[2:3], v[2:3], 0, s[6:7]
	v_cmp_lt_u64_e32 vcc, s[16:17], v[2:3]
	s_or_b64 s[14:15], vcc, s[14:15]
	v_lshl_add_u64 v[8:9], v[8:9], 0, s[12:13]
	s_waitcnt vmcnt(0)
	global_store_dwordx4 v[4:5], v[12:15], off
	s_nop 1
	v_cvt_pk_bf16_f32 v12, v12, v13
	v_cvt_pk_bf16_f32 v13, v14, v15
	v_lshl_add_u64 v[4:5], v[4:5], 0, s[8:9]
	global_store_dwordx2 v[6:7], v[12:13], off
	v_lshl_add_u64 v[6:7], v[6:7], 0, s[10:11]
	s_andn2_b64 exec, exec, s[14:15]
	s_cbranch_execz .LBB0_12

; DI void conv_job(const float* src, int ld, int K, int N, int kind, const float* gain, u16* dst, char* smem, int rank, int nwork) {
;     ...
;   for (int tile = rank; tile < tk_n * tn_n; tile += nwork) {
;     const int tk = tile % tk_n, tn = tile / tk_n;
;     const int k0 = tk * 128, n0 = tn * 64;
;     const int nn = tid & 63;
;     float cv[16];
; #pragma unroll
;     for (int i = 0; i < 16; ++i) cv[i] = conv_src(src, ld, kind, k0 + (tid >> 6) + 8 * i, n0 + nn);
;     if (gain) {
;       float gv[16];
; #pragma unroll
;       for (int i = 0; i < 16; ++i) gv[i] = gain[k0 + (tid >> 6) + 8 * i];
; #pragma unroll
;       for (int i = 0; i < 16; ++i) cv[i] *= gv[i];
;     }
; #pragma unroll
;     for (int i = 0; i < 16; ++i) lds[nn * 129 + (tid >> 6) + 8 * i] = cv[i];
;     __syncthreads();
;     {
;       const int n2 = tid >> 3, ks = (tid & 7) * 16;
;       const float* r = lds + n2 * 129 + ks;
;       u32x4 o0 = MK4(pack2(r[0], r[1]), pack2(r[2], r[3]), pack2(r[4], r[5]), pack2(r[6], r[7]));
;       u32x4 o1 = MK4(pack2(r[8], r[9]), pack2(r[10], r[11]), pack2(r[12], r[13]), pack2(r[14], r[15]));
;       u32x4* d4 = (u32x4*)(dst + (size_t)(n0 + n2) * K + k0 + ks);
;       d4[0] = o0; d4[1] = o1;
;     }
;     __syncthreads();
;   }
.LBB0_459:
	s_mul_hi_i32 s8, s18, 0x2e8ba2e9
	s_lshr_b32 s9, s8, 31
	s_ashr_i32 s8, s8, 2
	s_add_i32 s9, s8, s9
	s_mul_i32 s8, s9, 0xfffff500
	s_add_i32 s8, s14, s8
	s_lshl_b32 s9, s9, 6
	v_add_u32_e32 v2, s8, v5
	v_or_b32_e32 v0, s9, v4
	v_ashrrev_i32_e32 v1, 31, v0
	v_ashrrev_i32_e32 v3, 31, v2
	v_lshl_add_u64 v[0:1], v[0:1], 2, s[4:5]
	v_lshlrev_b64 v[10:11], 12, v[2:3]
	v_lshl_add_u64 v[10:11], v[0:1], 0, v[10:11]
	global_load_dword v3, v[10:11], off nt
	v_add_u32_e32 v10, 8, v2
	v_ashrrev_i32_e32 v11, 31, v10
	v_lshlrev_b64 v[10:11], 12, v[10:11]
	v_lshl_add_u64 v[10:11], v[0:1], 0, v[10:11]
	global_load_dword v9, v[10:11], off nt
	v_add_u32_e32 v10, 16, v2
	s_waitcnt vmcnt(20)
	v_add_u32_e32 v12, 24, v2
	v_ashrrev_i32_e32 v11, 31, v10
	v_ashrrev_i32_e32 v13, 31, v12
	v_lshlrev_b64 v[10:11], 12, v[10:11]
	v_lshlrev_b64 v[12:13], 12, v[12:13]
	v_lshl_add_u64 v[10:11], v[0:1], 0, v[10:11]
	v_lshl_add_u64 v[12:13], v[0:1], 0, v[12:13]
	global_load_dword v10, v[10:11], off nt
	s_add_i32 s18, s18, s22
	global_load_dword v11, v[12:13], off nt
	v_add_u32_e32 v12, 32, v2
	v_ashrrev_i32_e32 v13, 31, v12
	v_lshlrev_b64 v[12:13], 12, v[12:13]
	v_lshl_add_u64 v[12:13], v[0:1], 0, v[12:13]
	global_load_dword v14, v[12:13], off nt
	v_add_u32_e32 v12, 40, v2
	v_ashrrev_i32_e32 v13, 31, v12
	v_lshlrev_b64 v[12:13], 12, v[12:13]
	v_lshl_add_u64 v[12:13], v[0:1], 0, v[12:13]
	global_load_dword v15, v[12:13], off nt
	v_add_u32_e32 v12, 48, v2
	v_ashrrev_i32_e32 v13, 31, v12
	v_lshlrev_b64 v[12:13], 12, v[12:13]
	v_lshl_add_u64 v[12:13], v[0:1], 0, v[12:13]
	global_load_dword v16, v[12:13], off nt
	v_add_u32_e32 v12, 56, v2
	v_ashrrev_i32_e32 v13, 31, v12
	v_lshlrev_b64 v[12:13], 12, v[12:13]
	v_lshl_add_u64 v[12:13], v[0:1], 0, v[12:13]
	global_load_dword v17, v[12:13], off nt
	v_add_u32_e32 v12, 64, v2
	v_ashrrev_i32_e32 v13, 31, v12
	v_lshlrev_b64 v[12:13], 12, v[12:13]
	v_lshl_add_u64 v[12:13], v[0:1], 0, v[12:13]
	global_load_dword v18, v[12:13], off nt
	v_add_u32_e32 v12, 0x48, v2
	v_ashrrev_i32_e32 v13, 31, v12
	v_lshlrev_b64 v[12:13], 12, v[12:13]
	v_lshl_add_u64 v[12:13], v[0:1], 0, v[12:13]
	global_load_dword v19, v[12:13], off nt
	v_add_u32_e32 v12, 0x50, v2
	v_ashrrev_i32_e32 v13, 31, v12
	v_lshlrev_b64 v[12:13], 12, v[12:13]
	v_lshl_add_u64 v[12:13], v[0:1], 0, v[12:13]
	global_load_dword v20, v[12:13], off nt
	v_add_u32_e32 v12, 0x58, v2
	v_ashrrev_i32_e32 v13, 31, v12
	v_lshlrev_b64 v[12:13], 12, v[12:13]
	v_lshl_add_u64 v[12:13], v[0:1], 0, v[12:13]
	global_load_dword v21, v[12:13], off nt
	v_add_u32_e32 v12, 0x60, v2
	v_ashrrev_i32_e32 v13, 31, v12
	v_lshlrev_b64 v[12:13], 12, v[12:13]
	v_lshl_add_u64 v[12:13], v[0:1], 0, v[12:13]
	global_load_dword v22, v[12:13], off nt
	v_add_u32_e32 v12, 0x68, v2
	v_ashrrev_i32_e32 v13, 31, v12
	v_lshlrev_b64 v[12:13], 12, v[12:13]
	v_lshl_add_u64 v[12:13], v[0:1], 0, v[12:13]
	global_load_dword v23, v[12:13], off nt
	v_add_u32_e32 v12, 0x70, v2
	v_ashrrev_i32_e32 v13, 31, v12
	v_lshlrev_b64 v[12:13], 12, v[12:13]
	v_lshl_add_u64 v[12:13], v[0:1], 0, v[12:13]
	global_load_dword v24, v[12:13], off nt
	v_add_u32_e32 v12, 0x78, v2
	v_ashrrev_i32_e32 v13, 31, v12
	v_lshlrev_b64 v[12:13], 12, v[12:13]
	v_lshl_add_u64 v[0:1], v[0:1], 0, v[12:13]
	global_load_dword v0, v[0:1], off nt
	s_add_i32 s14, s14, s15
	s_waitcnt vmcnt(14)
	ds_write2_b32 v6, v3, v9 offset1:8
	s_waitcnt vmcnt(12)
	ds_write2_b32 v6, v10, v11 offset0:16 offset1:24
	s_waitcnt vmcnt(10)
	ds_write2_b32 v6, v14, v15 offset0:32 offset1:40
	s_waitcnt vmcnt(8)
	ds_write2_b32 v6, v16, v17 offset0:48 offset1:56
	s_waitcnt vmcnt(6)
	ds_write2_b32 v6, v18, v19 offset0:64 offset1:72
	s_waitcnt vmcnt(4)
	ds_write2_b32 v6, v20, v21 offset0:80 offset1:88
	s_waitcnt vmcnt(2)
	ds_write2_b32 v6, v22, v23 offset0:96 offset1:104
	s_waitcnt vmcnt(0)
	ds_write2_b32 v6, v24, v0 offset0:112 offset1:120
	s_waitcnt lgkmcnt(0)
	s_barrier
	ds_read2_b32 v[0:1], v8 offset1:1
	ds_read2_b32 v[2:3], v8 offset0:2 offset1:3
	ds_read2_b32 v[10:11], v8 offset0:6 offset1:7
	ds_read2_b32 v[12:13], v8 offset0:10 offset1:11
	ds_read2_b32 v[14:15], v8 offset0:14 offset1:15
	s_waitcnt lgkmcnt(4)
	v_cvt_pk_bf16_f32 v0, v0, v1
	s_waitcnt lgkmcnt(3)
	v_cvt_pk_bf16_f32 v1, v2, v3
	ds_read2_b32 v[2:3], v8 offset0:4 offset1:5
	v_add_u32_e32 v9, s9, v7
	s_ashr_i32 s9, s8, 31
	s_cmpk_lt_i32 s18, 0x160
	s_waitcnt lgkmcnt(0)
	v_cvt_pk_bf16_f32 v2, v2, v3
	v_cvt_pk_bf16_f32 v3, v10, v11
	ds_read2_b32 v[10:11], v8 offset0:8 offset1:9
	s_waitcnt lgkmcnt(0)
	v_cvt_pk_bf16_f32 v10, v10, v11
	v_cvt_pk_bf16_f32 v11, v12, v13
	ds_read2_b32 v[12:13], v8 offset0:12 offset1:13
	s_waitcnt lgkmcnt(0)
	v_cvt_pk_bf16_f32 v12, v12, v13
	v_cvt_pk_bf16_f32 v13, v14, v15
	v_mov_b64_e32 v[14:15], s[6:7]
	v_mad_i64_i32 v[14:15], s[20:21], v9, s11, v[14:15]
	v_lshl_add_u64 v[14:15], s[8:9], 1, v[14:15]
	v_lshl_add_u64 v[14:15], v[14:15], 0, v[164:165]
	global_store_dwordx4 v[14:15], v[0:3], off
	global_store_dwordx4 v[14:15], v[10:13], off offset:16
	s_barrier
	s_cbranch_scc1 .LBB0_459

; DI float conv_src(const float* src, int ld, int kind, int k, int n) {
;     ...
;   if (kind == CV_FFN) {
;     int tile = n >> 7, j = n & 127;
;     int col = j < 64 ? tile * 64 + j : DFF + tile * 64 + (j - 64);
;     return src[(size_t)k * ld + col];
; DI void conv_job(const float* src, int ld, int K, int N, int kind, const float* gain, u16* dst, char* smem, int rank, int nwork) {
;     ...
;   for (int tile = rank; tile < tk_n * tn_n; tile += nwork) {
;     const int tk = tile % tk_n, tn = tile / tk_n;
;     const int k0 = tk * 128, n0 = tn * 64;
;     const int nn = tid & 63;
;     float cv[16];
; #pragma unroll
;     for (int i = 0; i < 16; ++i) cv[i] = conv_src(src, ld, kind, k0 + (tid >> 6) + 8 * i, n0 + nn);
;     if (gain) {
;       float gv[16];
; #pragma unroll
;       for (int i = 0; i < 16; ++i) gv[i] = gain[k0 + (tid >> 6) + 8 * i];
; #pragma unroll
;       for (int i = 0; i < 16; ++i) cv[i] *= gv[i];
;     }
.LBB0_464:
	s_ashr_i32 s22, s21, 31
	s_lshr_b32 s22, s22, 29
	s_add_i32 s22, s21, s22
	s_ashr_i32 s26, s22, 3
	s_lshl_b32 s23, s26, 10
	s_lshl_b32 s22, s26, 6
	s_sub_i32 s27, s1, s23
	v_add_u32_e32 v16, s27, v19
	s_and_b32 s27, s22, 64
	s_cmp_eq_u32 s27, 0
	s_cselect_b64 vcc, -1, 0
	s_lshl_b32 s26, s26, 5
	v_or_b32_e32 v0, s27, v18
	s_andn2_b32 s26, s26, 63
	v_or_b32_e32 v1, s26, v0
	s_addk_i32 s26, 0xac0
	v_add_u32_e32 v0, s26, v0
	v_cndmask_b32_e32 v0, v0, v1, vcc
	v_ashrrev_i32_e32 v1, 31, v0
	s_waitcnt vmcnt(0)
	v_lshl_add_u64 v[24:25], v[0:1], 2, s[14:15]
	v_mad_i64_i32 v[0:1], s[26:27], v16, s28, v[24:25]
	global_load_dword v0, v[0:1], off nt
	v_add_u32_e32 v1, 8, v16
	v_mad_i64_i32 v[2:3], s[26:27], v1, s28, v[24:25]
	global_load_dword v1, v[2:3], off nt
	v_add_u32_e32 v2, 16, v16
	v_mad_i64_i32 v[2:3], s[26:27], v2, s28, v[24:25]
	global_load_dword v2, v[2:3], off nt
	v_add_u32_e32 v3, 24, v16
	v_mad_i64_i32 v[4:5], s[26:27], v3, s28, v[24:25]
	global_load_dword v3, v[4:5], off nt
	v_add_u32_e32 v4, 32, v16
	v_mad_i64_i32 v[4:5], s[26:27], v4, s28, v[24:25]
	global_load_dword v4, v[4:5], off nt
	v_add_u32_e32 v5, 40, v16
	v_mad_i64_i32 v[6:7], s[26:27], v5, s28, v[24:25]
	global_load_dword v5, v[6:7], off nt
	v_add_u32_e32 v6, 48, v16
	v_mad_i64_i32 v[6:7], s[26:27], v6, s28, v[24:25]
	global_load_dword v6, v[6:7], off nt
	v_add_u32_e32 v7, 56, v16
	v_mad_i64_i32 v[8:9], s[26:27], v7, s28, v[24:25]
	global_load_dword v7, v[8:9], off nt
	v_add_u32_e32 v8, 64, v16
	v_mad_i64_i32 v[8:9], s[26:27], v8, s28, v[24:25]
	global_load_dword v8, v[8:9], off nt
	v_add_u32_e32 v9, 0x48, v16
	v_mad_i64_i32 v[10:11], s[26:27], v9, s28, v[24:25]
	global_load_dword v9, v[10:11], off nt
	v_add_u32_e32 v10, 0x50, v16
	v_mad_i64_i32 v[10:11], s[26:27], v10, s28, v[24:25]
	global_load_dword v10, v[10:11], off nt
	v_add_u32_e32 v11, 0x58, v16
	v_mad_i64_i32 v[12:13], s[26:27], v11, s28, v[24:25]
	global_load_dword v11, v[12:13], off nt
	v_add_u32_e32 v12, 0x60, v16
	v_mad_i64_i32 v[12:13], s[26:27], v12, s28, v[24:25]
	global_load_dword v12, v[12:13], off nt
	v_add_u32_e32 v13, 0x68, v16
	v_mad_i64_i32 v[14:15], s[26:27], v13, s28, v[24:25]
	global_load_dword v13, v[14:15], off nt
	v_add_u32_e32 v14, 0x70, v16
	v_mad_i64_i32 v[14:15], s[26:27], v14, s28, v[24:25]
	global_load_dword v14, v[14:15], off nt
	v_add_u32_e32 v15, 0x78, v16
	v_mad_i64_i32 v[24:25], s[26:27], v15, s28, v[24:25]
	global_load_dword v15, v[24:25], off nt
	s_andn2_b64 vcc, exec, s[12:13]
	s_cbranch_vccnz .LBB0_463
	v_ashrrev_i32_e32 v17, 31, v16
	v_lshl_add_u64 v[16:17], v[16:17], 2, s[18:19]
	global_load_dword v24, v[16:17], off nt
	global_load_dword v25, v[16:17], off offset:32 nt
	global_load_dword v26, v[16:17], off offset:64 nt
	global_load_dword v27, v[16:17], off offset:96 nt
	global_load_dword v28, v[16:17], off offset:128 nt
	global_load_dword v29, v[16:17], off offset:160 nt
	global_load_dword v30, v[16:17], off offset:192 nt
	global_load_dword v31, v[16:17], off offset:224 nt
	global_load_dword v32, v[16:17], off offset:256 nt
	global_load_dword v33, v[16:17], off offset:288 nt
	global_load_dword v34, v[16:17], off offset:320 nt
	global_load_dword v35, v[16:17], off offset:352 nt
	global_load_dword v36, v[16:17], off offset:384 nt
	global_load_dword v37, v[16:17], off offset:416 nt
	global_load_dword v38, v[16:17], off offset:448 nt
	global_load_dword v39, v[16:17], off offset:480 nt
	s_waitcnt vmcnt(14)
	v_pk_mul_f32 v[0:1], v[0:1], v[24:25]
	s_waitcnt vmcnt(12)
	v_pk_mul_f32 v[2:3], v[2:3], v[26:27]
	s_waitcnt vmcnt(10)
	v_pk_mul_f32 v[4:5], v[4:5], v[28:29]
	s_waitcnt vmcnt(8)
	v_pk_mul_f32 v[6:7], v[6:7], v[30:31]
	s_waitcnt vmcnt(6)
	v_pk_mul_f32 v[8:9], v[8:9], v[32:33]
	s_waitcnt vmcnt(4)
	v_pk_mul_f32 v[10:11], v[10:11], v[34:35]
	s_waitcnt vmcnt(2)
	v_pk_mul_f32 v[12:13], v[12:13], v[36:37]
	s_waitcnt vmcnt(0)
	v_pk_mul_f32 v[14:15], v[14:15], v[38:39]
	s_branch .LBB0_463

; DI void conv_job(const float* src, int ld, int K, int N, int kind, const float* gain, u16* dst, char* smem, int rank, int nwork) {
;     ...
;   for (int tile = rank; tile < tk_n * tn_n; tile += nwork) {
;     const int tk = tile % tk_n, tn = tile / tk_n;
;     const int k0 = tk * 128, n0 = tn * 64;
;     const int nn = tid & 63;
;     float cv[16];
; #pragma unroll
;     for (int i = 0; i < 16; ++i) cv[i] = conv_src(src, ld, kind, k0 + (tid >> 6) + 8 * i, n0 + nn);
;     if (gain) {
;       float gv[16];
; #pragma unroll
;       for (int i = 0; i < 16; ++i) gv[i] = gain[k0 + (tid >> 6) + 8 * i];
; #pragma unroll
;       for (int i = 0; i < 16; ++i) cv[i] *= gv[i];
;     }
; #pragma unroll
;     for (int i = 0; i < 16; ++i) lds[nn * 129 + (tid >> 6) + 8 * i] = cv[i];
;     __syncthreads();
;     {
;       const int n2 = tid >> 3, ks = (tid & 7) * 16;
;       const float* r = lds + n2 * 129 + ks;
;       u32x4 o0 = MK4(pack2(r[0], r[1]), pack2(r[2], r[3]), pack2(r[4], r[5]), pack2(r[6], r[7]));
;       u32x4 o1 = MK4(pack2(r[8], r[9]), pack2(r[10], r[11]), pack2(r[12], r[13]), pack2(r[14], r[15]));
;       u32x4* d4 = (u32x4*)(dst + (size_t)(n0 + n2) * K + k0 + ks);
;       d4[0] = o0; d4[1] = o1;
;     }
;     __syncthreads();
;   }
.LBB0_468:
	s_mul_hi_i32 s20, s23, 0x2e8ba2e9
	s_lshr_b32 s21, s20, 31
	s_ashr_i32 s20, s20, 2
	s_add_i32 s21, s20, s21
	s_mul_i32 s20, s21, 0xfffff500
	s_add_i32 s20, s1, s20
	s_lshl_b32 s21, s21, 6
	v_add_u32_e32 v2, s20, v5
	v_or_b32_e32 v0, s21, v4
	v_ashrrev_i32_e32 v1, 31, v0
	v_ashrrev_i32_e32 v3, 31, v2
	v_lshl_add_u64 v[0:1], v[0:1], 2, s[14:15]
	v_lshlrev_b64 v[10:11], 12, v[2:3]
	v_lshl_add_u64 v[10:11], v[0:1], 0, v[10:11]
	global_load_dword v3, v[10:11], off nt
	v_add_u32_e32 v10, 8, v2
	v_ashrrev_i32_e32 v11, 31, v10
	v_lshlrev_b64 v[10:11], 12, v[10:11]
	v_lshl_add_u64 v[10:11], v[0:1], 0, v[10:11]
	global_load_dword v9, v[10:11], off nt
	v_add_u32_e32 v10, 16, v2
	s_waitcnt vmcnt(20)
	v_add_u32_e32 v12, 24, v2
	v_ashrrev_i32_e32 v11, 31, v10
	v_ashrrev_i32_e32 v13, 31, v12
	v_lshlrev_b64 v[10:11], 12, v[10:11]
	v_lshlrev_b64 v[12:13], 12, v[12:13]
	v_lshl_add_u64 v[10:11], v[0:1], 0, v[10:11]
	v_lshl_add_u64 v[12:13], v[0:1], 0, v[12:13]
	global_load_dword v10, v[10:11], off nt
	s_add_i32 s23, s23, s42
	global_load_dword v11, v[12:13], off nt
	v_add_u32_e32 v12, 32, v2
	v_ashrrev_i32_e32 v13, 31, v12
	v_lshlrev_b64 v[12:13], 12, v[12:13]
	v_lshl_add_u64 v[12:13], v[0:1], 0, v[12:13]
	global_load_dword v14, v[12:13], off nt
	v_add_u32_e32 v12, 40, v2
	v_ashrrev_i32_e32 v13, 31, v12
	v_lshlrev_b64 v[12:13], 12, v[12:13]
	v_lshl_add_u64 v[12:13], v[0:1], 0, v[12:13]
	global_load_dword v15, v[12:13], off nt
	v_add_u32_e32 v12, 48, v2
	v_ashrrev_i32_e32 v13, 31, v12
	v_lshlrev_b64 v[12:13], 12, v[12:13]
	v_lshl_add_u64 v[12:13], v[0:1], 0, v[12:13]
	global_load_dword v16, v[12:13], off nt
	v_add_u32_e32 v12, 56, v2
	v_ashrrev_i32_e32 v13, 31, v12
	v_lshlrev_b64 v[12:13], 12, v[12:13]
	v_lshl_add_u64 v[12:13], v[0:1], 0, v[12:13]
	global_load_dword v17, v[12:13], off nt
	v_add_u32_e32 v12, 64, v2
	v_ashrrev_i32_e32 v13, 31, v12
	v_lshlrev_b64 v[12:13], 12, v[12:13]
	v_lshl_add_u64 v[12:13], v[0:1], 0, v[12:13]
	global_load_dword v18, v[12:13], off nt
	v_add_u32_e32 v12, 0x48, v2
	v_ashrrev_i32_e32 v13, 31, v12
	v_lshlrev_b64 v[12:13], 12, v[12:13]
	v_lshl_add_u64 v[12:13], v[0:1], 0, v[12:13]
	global_load_dword v19, v[12:13], off nt
	v_add_u32_e32 v12, 0x50, v2
	v_ashrrev_i32_e32 v13, 31, v12
	v_lshlrev_b64 v[12:13], 12, v[12:13]
	v_lshl_add_u64 v[12:13], v[0:1], 0, v[12:13]
	global_load_dword v20, v[12:13], off nt
	v_add_u32_e32 v12, 0x58, v2
	v_ashrrev_i32_e32 v13, 31, v12
	v_lshlrev_b64 v[12:13], 12, v[12:13]
	v_lshl_add_u64 v[12:13], v[0:1], 0, v[12:13]
	global_load_dword v21, v[12:13], off nt
	v_add_u32_e32 v12, 0x60, v2
	v_ashrrev_i32_e32 v13, 31, v12
	v_lshlrev_b64 v[12:13], 12, v[12:13]
	v_lshl_add_u64 v[12:13], v[0:1], 0, v[12:13]
	global_load_dword v22, v[12:13], off nt
	v_add_u32_e32 v12, 0x68, v2
	v_ashrrev_i32_e32 v13, 31, v12
	v_lshlrev_b64 v[12:13], 12, v[12:13]
	v_lshl_add_u64 v[12:13], v[0:1], 0, v[12:13]
	global_load_dword v23, v[12:13], off nt
	v_add_u32_e32 v12, 0x70, v2
	v_ashrrev_i32_e32 v13, 31, v12
	v_lshlrev_b64 v[12:13], 12, v[12:13]
	v_lshl_add_u64 v[12:13], v[0:1], 0, v[12:13]
	global_load_dword v24, v[12:13], off nt
	v_add_u32_e32 v12, 0x78, v2
	v_ashrrev_i32_e32 v13, 31, v12
	v_lshlrev_b64 v[12:13], 12, v[12:13]
	v_lshl_add_u64 v[0:1], v[0:1], 0, v[12:13]
	global_load_dword v0, v[0:1], off nt
	s_add_i32 s1, s1, s22
	s_waitcnt vmcnt(14)
	ds_write2_b32 v6, v3, v9 offset1:8
	s_waitcnt vmcnt(12)
	ds_write2_b32 v6, v10, v11 offset0:16 offset1:24
	s_waitcnt vmcnt(10)
	ds_write2_b32 v6, v14, v15 offset0:32 offset1:40
	s_waitcnt vmcnt(8)
	ds_write2_b32 v6, v16, v17 offset0:48 offset1:56
	s_waitcnt vmcnt(6)
	ds_write2_b32 v6, v18, v19 offset0:64 offset1:72
	s_waitcnt vmcnt(4)
	ds_write2_b32 v6, v20, v21 offset0:80 offset1:88
	s_waitcnt vmcnt(2)
	ds_write2_b32 v6, v22, v23 offset0:96 offset1:104
	s_waitcnt vmcnt(0)
	ds_write2_b32 v6, v24, v0 offset0:112 offset1:120
	s_waitcnt lgkmcnt(0)
	s_barrier
	ds_read2_b32 v[0:1], v8 offset1:1
	ds_read2_b32 v[2:3], v8 offset0:2 offset1:3
	ds_read2_b32 v[10:11], v8 offset0:6 offset1:7
	ds_read2_b32 v[12:13], v8 offset0:10 offset1:11
	ds_read2_b32 v[14:15], v8 offset0:14 offset1:15
	s_waitcnt lgkmcnt(4)
	v_cvt_pk_bf16_f32 v0, v0, v1
	s_waitcnt lgkmcnt(3)
	v_cvt_pk_bf16_f32 v1, v2, v3
	ds_read2_b32 v[2:3], v8 offset0:4 offset1:5
	v_add_u32_e32 v9, s21, v7
	s_ashr_i32 s21, s20, 31
	s_cmpk_lt_i32 s23, 0x160
	s_waitcnt lgkmcnt(0)
	v_cvt_pk_bf16_f32 v2, v2, v3
	v_cvt_pk_bf16_f32 v3, v10, v11
	ds_read2_b32 v[10:11], v8 offset0:8 offset1:9
	s_waitcnt lgkmcnt(0)
	v_cvt_pk_bf16_f32 v10, v10, v11
	v_cvt_pk_bf16_f32 v11, v12, v13
	ds_read2_b32 v[12:13], v8 offset0:12 offset1:13
	s_waitcnt lgkmcnt(0)
	v_cvt_pk_bf16_f32 v12, v12, v13
	v_cvt_pk_bf16_f32 v13, v14, v15
	v_mov_b64_e32 v[14:15], s[18:19]
	v_mad_i64_i32 v[14:15], s[26:27], v9, s11, v[14:15]
	v_lshl_add_u64 v[14:15], s[20:21], 1, v[14:15]
	v_lshl_add_u64 v[14:15], v[14:15], 0, v[164:165]
	global_store_dwordx4 v[14:15], v[0:3], off
	global_store_dwordx4 v[14:15], v[10:13], off offset:16
	s_barrier
	s_cbranch_scc1 .LBB0_468

; DI float conv_src(const float* src, int ld, int kind, int k, int n) {
;     ...
;   if (kind == CV_FFN) {
;     int tile = n >> 7, j = n & 127;
;     int col = j < 64 ? tile * 64 + j : DFF + tile * 64 + (j - 64);
;     return src[(size_t)k * ld + col];
; DI void conv_job(const float* src, int ld, int K, int N, int kind, const float* gain, u16* dst, char* smem, int rank, int nwork) {
;     ...
;   for (int tile = rank; tile < tk_n * tn_n; tile += nwork) {
;     const int tk = tile % tk_n, tn = tile / tk_n;
;     const int k0 = tk * 128, n0 = tn * 64;
;     const int nn = tid & 63;
;     float cv[16];
; #pragma unroll
;     for (int i = 0; i < 16; ++i) cv[i] = conv_src(src, ld, kind, k0 + (tid >> 6) + 8 * i, n0 + nn);
;     if (gain) {
;       float gv[16];
; #pragma unroll
;       for (int i = 0; i < 16; ++i) gv[i] = gain[k0 + (tid >> 6) + 8 * i];
; #pragma unroll
;       for (int i = 0; i < 16; ++i) cv[i] *= gv[i];
;     }
.LBB0_472:
	s_ashr_i32 s20, s19, 31
	s_lshr_b32 s20, s20, 29
	s_add_i32 s20, s19, s20
	s_ashr_i32 s22, s20, 3
	s_lshl_b32 s21, s22, 10
	s_lshl_b32 s20, s22, 6
	s_sub_i32 s23, s1, s21
	v_add_u32_e32 v16, s23, v19
	s_and_b32 s23, s20, 64
	s_cmp_eq_u32 s23, 0
	s_cselect_b64 vcc, -1, 0
	s_lshl_b32 s22, s22, 5
	v_or_b32_e32 v0, s23, v18
	s_andn2_b32 s22, s22, 63
	v_or_b32_e32 v1, s22, v0
	s_addk_i32 s22, 0xac0
	v_add_u32_e32 v0, s22, v0
	v_cndmask_b32_e32 v0, v0, v1, vcc
	v_ashrrev_i32_e32 v1, 31, v0
	s_waitcnt vmcnt(0)
	v_lshl_add_u64 v[24:25], v[0:1], 2, s[6:7]
	v_mad_i64_i32 v[0:1], s[22:23], v16, s28, v[24:25]
	global_load_dword v0, v[0:1], off nt
	v_add_u32_e32 v1, 8, v16
	v_mad_i64_i32 v[2:3], s[22:23], v1, s28, v[24:25]
	global_load_dword v1, v[2:3], off nt
	v_add_u32_e32 v2, 16, v16
	v_mad_i64_i32 v[2:3], s[22:23], v2, s28, v[24:25]
	global_load_dword v2, v[2:3], off nt
	v_add_u32_e32 v3, 24, v16
	v_mad_i64_i32 v[4:5], s[22:23], v3, s28, v[24:25]
	global_load_dword v3, v[4:5], off nt
	v_add_u32_e32 v4, 32, v16
	v_mad_i64_i32 v[4:5], s[22:23], v4, s28, v[24:25]
	global_load_dword v4, v[4:5], off nt
	v_add_u32_e32 v5, 40, v16
	v_mad_i64_i32 v[6:7], s[22:23], v5, s28, v[24:25]
	global_load_dword v5, v[6:7], off nt
	v_add_u32_e32 v6, 48, v16
	v_mad_i64_i32 v[6:7], s[22:23], v6, s28, v[24:25]
	global_load_dword v6, v[6:7], off nt
	v_add_u32_e32 v7, 56, v16
	v_mad_i64_i32 v[8:9], s[22:23], v7, s28, v[24:25]
	global_load_dword v7, v[8:9], off nt
	v_add_u32_e32 v8, 64, v16
	v_mad_i64_i32 v[8:9], s[22:23], v8, s28, v[24:25]
	global_load_dword v8, v[8:9], off nt
	v_add_u32_e32 v9, 0x48, v16
	v_mad_i64_i32 v[10:11], s[22:23], v9, s28, v[24:25]
	global_load_dword v9, v[10:11], off nt
	v_add_u32_e32 v10, 0x50, v16
	v_mad_i64_i32 v[10:11], s[22:23], v10, s28, v[24:25]
	global_load_dword v10, v[10:11], off nt
	v_add_u32_e32 v11, 0x58, v16
	v_mad_i64_i32 v[12:13], s[22:23], v11, s28, v[24:25]
	global_load_dword v11, v[12:13], off nt
	v_add_u32_e32 v12, 0x60, v16
	v_mad_i64_i32 v[12:13], s[22:23], v12, s28, v[24:25]
	global_load_dword v12, v[12:13], off nt
	v_add_u32_e32 v13, 0x68, v16
	v_mad_i64_i32 v[14:15], s[22:23], v13, s28, v[24:25]
	global_load_dword v13, v[14:15], off nt
	v_add_u32_e32 v14, 0x70, v16
	v_mad_i64_i32 v[14:15], s[22:23], v14, s28, v[24:25]
	global_load_dword v14, v[14:15], off nt
	v_add_u32_e32 v15, 0x78, v16
	v_mad_i64_i32 v[24:25], s[22:23], v15, s28, v[24:25]
	global_load_dword v15, v[24:25], off nt
	s_andn2_b64 vcc, exec, s[16:17]
	s_cbranch_vccnz .LBB0_471
	v_ashrrev_i32_e32 v17, 31, v16
	v_lshl_add_u64 v[16:17], v[16:17], 2, s[8:9]
	global_load_dword v24, v[16:17], off nt
	global_load_dword v25, v[16:17], off offset:32 nt
	global_load_dword v26, v[16:17], off offset:64 nt
	global_load_dword v27, v[16:17], off offset:96 nt
	global_load_dword v28, v[16:17], off offset:128 nt
	global_load_dword v29, v[16:17], off offset:160 nt
	global_load_dword v30, v[16:17], off offset:192 nt
	global_load_dword v31, v[16:17], off offset:224 nt
	global_load_dword v32, v[16:17], off offset:256 nt
	global_load_dword v33, v[16:17], off offset:288 nt
	global_load_dword v34, v[16:17], off offset:320 nt
	global_load_dword v35, v[16:17], off offset:352 nt
	global_load_dword v36, v[16:17], off offset:384 nt
	global_load_dword v37, v[16:17], off offset:416 nt
	global_load_dword v38, v[16:17], off offset:448 nt
	global_load_dword v39, v[16:17], off offset:480 nt
	s_waitcnt vmcnt(14)
	v_pk_mul_f32 v[0:1], v[0:1], v[24:25]
	s_waitcnt vmcnt(12)
	v_pk_mul_f32 v[2:3], v[2:3], v[26:27]
	s_waitcnt vmcnt(10)
	v_pk_mul_f32 v[4:5], v[4:5], v[28:29]
	s_waitcnt vmcnt(8)
	v_pk_mul_f32 v[6:7], v[6:7], v[30:31]
	s_waitcnt vmcnt(6)
	v_pk_mul_f32 v[8:9], v[8:9], v[32:33]
	s_waitcnt vmcnt(4)
	v_pk_mul_f32 v[10:11], v[10:11], v[34:35]
	s_waitcnt vmcnt(2)
	v_pk_mul_f32 v[12:13], v[12:13], v[36:37]
	s_waitcnt vmcnt(0)
	v_pk_mul_f32 v[14:15], v[14:15], v[38:39]
	s_branch .LBB0_471

; DI void conv_job(const float* src, int ld, int K, int N, int kind, const float* gain, u16* dst, char* smem, int rank, int nwork) {
;     ...
;   for (int tile = rank; tile < tk_n * tn_n; tile += nwork) {
;     const int tk = tile % tk_n, tn = tile / tk_n;
;     const int k0 = tk * 128, n0 = tn * 64;
;     const int nn = tid & 63;
;     float cv[16];
; #pragma unroll
;     for (int i = 0; i < 16; ++i) cv[i] = conv_src(src, ld, kind, k0 + (tid >> 6) + 8 * i, n0 + nn);
;     if (gain) {
;       float gv[16];
; #pragma unroll
;       for (int i = 0; i < 16; ++i) gv[i] = gain[k0 + (tid >> 6) + 8 * i];
; #pragma unroll
;       for (int i = 0; i < 16; ++i) cv[i] *= gv[i];
;     }
; #pragma unroll
;     for (int i = 0; i < 16; ++i) lds[nn * 129 + (tid >> 6) + 8 * i] = cv[i];
;     __syncthreads();
;     {
;       const int n2 = tid >> 3, ks = (tid & 7) * 16;
;       const float* r = lds + n2 * 129 + ks;
;       u32x4 o0 = MK4(pack2(r[0], r[1]), pack2(r[2], r[3]), pack2(r[4], r[5]), pack2(r[6], r[7]));
;       u32x4 o1 = MK4(pack2(r[8], r[9]), pack2(r[10], r[11]), pack2(r[12], r[13]), pack2(r[14], r[15]));
;       u32x4* d4 = (u32x4*)(dst + (size_t)(n0 + n2) * K + k0 + ks);
;       d4[0] = o0; d4[1] = o1;
;     }
;     __syncthreads();
;   }
.LBB0_476:
	s_ashr_i32 s14, s19, 31
	s_lshr_b32 s14, s14, 29
	s_add_i32 s14, s19, s14
	s_ashr_i32 s15, s14, 3
	s_lshl_b32 s14, s15, 10
	s_sub_i32 s14, s1, s14
	s_lshl_b32 s15, s15, 6
	v_add_u32_e32 v2, s14, v5
	v_or_b32_e32 v0, s15, v4
	v_ashrrev_i32_e32 v1, 31, v0
	v_ashrrev_i32_e32 v3, 31, v2
	v_lshl_add_u64 v[0:1], v[0:1], 2, s[8:9]
	v_lshlrev_b64 v[10:11], 12, v[2:3]
	v_lshl_add_u64 v[10:11], v[0:1], 0, v[10:11]
	global_load_dword v3, v[10:11], off nt
	v_add_u32_e32 v10, 8, v2
	v_ashrrev_i32_e32 v11, 31, v10
	v_lshlrev_b64 v[10:11], 12, v[10:11]
	v_lshl_add_u64 v[10:11], v[0:1], 0, v[10:11]
	global_load_dword v9, v[10:11], off nt
	v_add_u32_e32 v10, 16, v2
	s_waitcnt vmcnt(20)
	v_add_u32_e32 v12, 24, v2
	v_ashrrev_i32_e32 v11, 31, v10
	v_ashrrev_i32_e32 v13, 31, v12
	v_lshlrev_b64 v[10:11], 12, v[10:11]
	v_lshlrev_b64 v[12:13], 12, v[12:13]
	v_lshl_add_u64 v[10:11], v[0:1], 0, v[10:11]
	v_lshl_add_u64 v[12:13], v[0:1], 0, v[12:13]
	global_load_dword v10, v[10:11], off nt
	s_add_i32 s19, s19, s22
	global_load_dword v11, v[12:13], off nt
	v_add_u32_e32 v12, 32, v2
	v_ashrrev_i32_e32 v13, 31, v12
	v_lshlrev_b64 v[12:13], 12, v[12:13]
	v_lshl_add_u64 v[12:13], v[0:1], 0, v[12:13]
	global_load_dword v14, v[12:13], off nt
	v_add_u32_e32 v12, 40, v2
	v_ashrrev_i32_e32 v13, 31, v12
	v_lshlrev_b64 v[12:13], 12, v[12:13]
	v_lshl_add_u64 v[12:13], v[0:1], 0, v[12:13]
	global_load_dword v15, v[12:13], off nt
	v_add_u32_e32 v12, 48, v2
	v_ashrrev_i32_e32 v13, 31, v12
	v_lshlrev_b64 v[12:13], 12, v[12:13]
	v_lshl_add_u64 v[12:13], v[0:1], 0, v[12:13]
	global_load_dword v16, v[12:13], off nt
	v_add_u32_e32 v12, 56, v2
	v_ashrrev_i32_e32 v13, 31, v12
	v_lshlrev_b64 v[12:13], 12, v[12:13]
	v_lshl_add_u64 v[12:13], v[0:1], 0, v[12:13]
	global_load_dword v17, v[12:13], off nt
	v_add_u32_e32 v12, 64, v2
	v_ashrrev_i32_e32 v13, 31, v12
	v_lshlrev_b64 v[12:13], 12, v[12:13]
	v_lshl_add_u64 v[12:13], v[0:1], 0, v[12:13]
	global_load_dword v18, v[12:13], off nt
	v_add_u32_e32 v12, 0x48, v2
	v_ashrrev_i32_e32 v13, 31, v12
	v_lshlrev_b64 v[12:13], 12, v[12:13]
	v_lshl_add_u64 v[12:13], v[0:1], 0, v[12:13]
	global_load_dword v19, v[12:13], off nt
	v_add_u32_e32 v12, 0x50, v2
	v_ashrrev_i32_e32 v13, 31, v12
	v_lshlrev_b64 v[12:13], 12, v[12:13]
	v_lshl_add_u64 v[12:13], v[0:1], 0, v[12:13]
	global_load_dword v20, v[12:13], off nt
	v_add_u32_e32 v12, 0x58, v2
	v_ashrrev_i32_e32 v13, 31, v12
	v_lshlrev_b64 v[12:13], 12, v[12:13]
	v_lshl_add_u64 v[12:13], v[0:1], 0, v[12:13]
	global_load_dword v21, v[12:13], off nt
	v_add_u32_e32 v12, 0x60, v2
	v_ashrrev_i32_e32 v13, 31, v12
	v_lshlrev_b64 v[12:13], 12, v[12:13]
	v_lshl_add_u64 v[12:13], v[0:1], 0, v[12:13]
	global_load_dword v22, v[12:13], off nt
	v_add_u32_e32 v12, 0x68, v2
	v_ashrrev_i32_e32 v13, 31, v12
	v_lshlrev_b64 v[12:13], 12, v[12:13]
	v_lshl_add_u64 v[12:13], v[0:1], 0, v[12:13]
	global_load_dword v23, v[12:13], off nt
	v_add_u32_e32 v12, 0x70, v2
	v_ashrrev_i32_e32 v13, 31, v12
	v_lshlrev_b64 v[12:13], 12, v[12:13]
	v_lshl_add_u64 v[12:13], v[0:1], 0, v[12:13]
	global_load_dword v24, v[12:13], off nt
	v_add_u32_e32 v12, 0x78, v2
	v_ashrrev_i32_e32 v13, 31, v12
	v_lshlrev_b64 v[12:13], 12, v[12:13]
	v_lshl_add_u64 v[0:1], v[0:1], 0, v[12:13]
	global_load_dword v0, v[0:1], off nt
	s_add_i32 s1, s1, s18
	s_waitcnt vmcnt(14)
	ds_write2_b32 v6, v3, v9 offset1:8
	s_waitcnt vmcnt(12)
	ds_write2_b32 v6, v10, v11 offset0:16 offset1:24
	s_waitcnt vmcnt(10)
	ds_write2_b32 v6, v14, v15 offset0:32 offset1:40
	s_waitcnt vmcnt(8)
	ds_write2_b32 v6, v16, v17 offset0:48 offset1:56
	s_waitcnt vmcnt(6)
	ds_write2_b32 v6, v18, v19 offset0:64 offset1:72
	s_waitcnt vmcnt(4)
	ds_write2_b32 v6, v20, v21 offset0:80 offset1:88
	s_waitcnt vmcnt(2)
	ds_write2_b32 v6, v22, v23 offset0:96 offset1:104
	s_waitcnt vmcnt(0)
	ds_write2_b32 v6, v24, v0 offset0:112 offset1:120
	s_waitcnt lgkmcnt(0)
	s_barrier
	ds_read2_b32 v[0:1], v8 offset1:1
	ds_read2_b32 v[2:3], v8 offset0:2 offset1:3
	ds_read2_b32 v[10:11], v8 offset0:6 offset1:7
	ds_read2_b32 v[12:13], v8 offset0:10 offset1:11
	ds_read2_b32 v[14:15], v8 offset0:14 offset1:15
	s_waitcnt lgkmcnt(4)
	v_cvt_pk_bf16_f32 v0, v0, v1
	s_waitcnt lgkmcnt(3)
	v_cvt_pk_bf16_f32 v1, v2, v3
	ds_read2_b32 v[2:3], v8 offset0:4 offset1:5
	s_waitcnt lgkmcnt(0)
	v_cvt_pk_bf16_f32 v2, v2, v3
	v_cvt_pk_bf16_f32 v3, v10, v11
	ds_read2_b32 v[10:11], v8 offset0:8 offset1:9
	s_waitcnt lgkmcnt(0)
	v_cvt_pk_bf16_f32 v10, v10, v11
	v_cvt_pk_bf16_f32 v11, v12, v13
	ds_read2_b32 v[12:13], v8 offset0:12 offset1:13
	s_waitcnt lgkmcnt(0)
	v_cvt_pk_bf16_f32 v12, v12, v13
	v_cvt_pk_bf16_f32 v13, v14, v15
	v_add_u32_e32 v14, s15, v7
	v_ashrrev_i32_e32 v15, 31, v14
	v_lshlrev_b64 v[14:15], 11, v[14:15]
	v_lshl_add_u64 v[14:15], s[98:99], 0, v[14:15]
	s_ashr_i32 s15, s14, 31
	v_lshl_add_u64 v[14:15], s[14:15], 1, v[14:15]
	v_lshl_add_u64 v[14:15], v[14:15], 0, v[164:165]
	s_cmpk_lt_i32 s19, 0x80
	global_store_dwordx4 v[14:15], v[0:3], off
	global_store_dwordx4 v[14:15], v[10:13], off offset:16
	s_barrier
	s_cbranch_scc1 .LBB0_476

; DI float conv_src(const float* src, int ld, int kind, int k, int n) {
;     ...
;   if (kind == CV_PAD) return n < ld ? src[(size_t)k * ld + n] : 0.f;
; DI void conv_job(const float* src, int ld, int K, int N, int kind, const float* gain, u16* dst, char* smem, int rank, int nwork) {
;     ...
;   for (int tile = rank; tile < tk_n * tn_n; tile += nwork) {
;     const int tk = tile % tk_n, tn = tile / tk_n;
;     const int k0 = tk * 128, n0 = tn * 64;
;     const int nn = tid & 63;
;     float cv[16];
; #pragma unroll
;     for (int i = 0; i < 16; ++i) cv[i] = conv_src(src, ld, kind, k0 + (tid >> 6) + 8 * i, n0 + nn);
;     if (gain) {
;       float gv[16];
; #pragma unroll
;       for (int i = 0; i < 16; ++i) gv[i] = gain[k0 + (tid >> 6) + 8 * i];
; #pragma unroll
;       for (int i = 0; i < 16; ++i) cv[i] *= gv[i];
;     }
.LBB0_482:
	s_ashr_i32 s14, s20, 31
	s_lshr_b32 s14, s14, 29
	s_add_i32 s14, s20, s14
	s_ashr_i32 s14, s14, 3
	s_lshl_b32 s22, s14, 10
	s_lshl_b32 s21, s14, 6
	s_sub_i32 s14, s18, s22
	v_or_b32_e32 v0, s21, v20
	v_readlane_b32 s40, v252, 27
	v_add_u32_e32 v8, s14, v21
	s_movk_i32 s14, 0x248
	v_ashrrev_i32_e32 v1, 31, v0
	v_readlane_b32 s54, v252, 41
	v_readlane_b32 s55, v252, 42
	v_cmp_gt_i32_e32 vcc, s14, v0
	v_readlane_b32 s41, v252, 28
	v_lshl_add_u64 v[12:13], v[0:1], 2, s[54:55]
	v_mov_b32_e32 v1, 0
	v_mov_b32_e32 v0, 0
	v_readlane_b32 s42, v252, 29
	v_readlane_b32 s43, v252, 30
	v_readlane_b32 s44, v252, 31
	v_readlane_b32 s45, v252, 32
	v_readlane_b32 s46, v252, 33
	v_readlane_b32 s47, v252, 34
	v_readlane_b32 s48, v252, 35
	v_readlane_b32 s49, v252, 36
	v_readlane_b32 s50, v252, 37
	v_readlane_b32 s51, v252, 38
	v_readlane_b32 s52, v252, 39
	v_readlane_b32 s53, v252, 40
	s_and_saveexec_b64 s[14:15], vcc
	s_cbranch_execz .LBB0_484
	s_movk_i32 s16, 0x920
	v_mad_i64_i32 v[2:3], s[26:27], v8, s16, v[12:13]
	global_load_dword v0, v[2:3], off nt
.LBB0_484:
	s_or_b64 exec, exec, s[14:15]
	s_and_saveexec_b64 s[14:15], vcc
	s_cbranch_execz .LBB0_486
	v_add_u32_e32 v1, 8, v8
	s_movk_i32 s16, 0x920
	v_mad_i64_i32 v[2:3], s[26:27], v1, s16, v[12:13]
	global_load_dword v1, v[2:3], off nt
.LBB0_486:
	s_or_b64 exec, exec, s[14:15]
	v_mov_b32_e32 v3, 0
	v_mov_b32_e32 v2, 0
	s_and_saveexec_b64 s[14:15], vcc
	s_cbranch_execz .LBB0_488
	v_add_u32_e32 v2, 16, v8
	s_movk_i32 s16, 0x920
	v_mad_i64_i32 v[4:5], s[26:27], v2, s16, v[12:13]
	global_load_dword v2, v[4:5], off nt
.LBB0_488:
	s_or_b64 exec, exec, s[14:15]
	s_and_saveexec_b64 s[14:15], vcc
	s_cbranch_execz .LBB0_490
	v_add_u32_e32 v3, 24, v8
	s_movk_i32 s16, 0x920
	v_mad_i64_i32 v[4:5], s[26:27], v3, s16, v[12:13]
	global_load_dword v3, v[4:5], off nt
.LBB0_490:
	s_or_b64 exec, exec, s[14:15]
	v_mov_b32_e32 v5, 0
	v_mov_b32_e32 v4, 0
	s_and_saveexec_b64 s[14:15], vcc
	s_cbranch_execz .LBB0_492
	v_add_u32_e32 v4, 32, v8
	s_movk_i32 s16, 0x920
	v_mad_i64_i32 v[6:7], s[26:27], v4, s16, v[12:13]
	global_load_dword v4, v[6:7], off nt
.LBB0_492:
	s_or_b64 exec, exec, s[14:15]
	s_and_saveexec_b64 s[14:15], vcc
	s_cbranch_execz .LBB0_494
	v_add_u32_e32 v5, 40, v8
	s_movk_i32 s16, 0x920
	v_mad_i64_i32 v[6:7], s[26:27], v5, s16, v[12:13]
	global_load_dword v5, v[6:7], off nt
.LBB0_494:
	s_or_b64 exec, exec, s[14:15]
	v_mov_b32_e32 v7, 0
	v_mov_b32_e32 v6, 0
	s_and_saveexec_b64 s[14:15], vcc
	s_cbranch_execz .LBB0_496
	v_add_u32_e32 v6, 48, v8
	s_movk_i32 s16, 0x920
	v_mad_i64_i32 v[10:11], s[26:27], v6, s16, v[12:13]
	global_load_dword v6, v[10:11], off nt
.LBB0_496:
	s_or_b64 exec, exec, s[14:15]
	s_and_saveexec_b64 s[14:15], vcc
	s_cbranch_execz .LBB0_498
	v_add_u32_e32 v7, 56, v8
	s_movk_i32 s16, 0x920
	v_mad_i64_i32 v[10:11], s[26:27], v7, s16, v[12:13]
	global_load_dword v7, v[10:11], off nt
.LBB0_498:
	s_or_b64 exec, exec, s[14:15]
	v_mov_b32_e32 v11, 0
	v_mov_b32_e32 v10, 0
	s_and_saveexec_b64 s[14:15], vcc
	s_cbranch_execz .LBB0_500
	v_add_u32_e32 v9, 64, v8
	s_movk_i32 s16, 0x920
	v_mad_i64_i32 v[14:15], s[26:27], v9, s16, v[12:13]
	global_load_dword v10, v[14:15], off nt
.LBB0_500:
	s_or_b64 exec, exec, s[14:15]
	s_and_saveexec_b64 s[14:15], vcc
	s_cbranch_execz .LBB0_502
	v_add_u32_e32 v9, 0x48, v8
	s_movk_i32 s16, 0x920
	v_mad_i64_i32 v[14:15], s[26:27], v9, s16, v[12:13]
	global_load_dword v11, v[14:15], off nt
.LBB0_502:
	s_or_b64 exec, exec, s[14:15]
	v_mov_b32_e32 v15, 0
	v_mov_b32_e32 v14, 0
	s_and_saveexec_b64 s[14:15], vcc
	s_cbranch_execz .LBB0_504
	v_add_u32_e32 v9, 0x50, v8
	s_movk_i32 s16, 0x920
	v_mad_i64_i32 v[16:17], s[26:27], v9, s16, v[12:13]
	global_load_dword v14, v[16:17], off nt
.LBB0_504:
	s_or_b64 exec, exec, s[14:15]
	s_and_saveexec_b64 s[14:15], vcc
	s_cbranch_execz .LBB0_506
	v_add_u32_e32 v9, 0x58, v8
	s_movk_i32 s16, 0x920
	v_mad_i64_i32 v[16:17], s[26:27], v9, s16, v[12:13]
	global_load_dword v15, v[16:17], off nt
.LBB0_506:
	s_or_b64 exec, exec, s[14:15]
	v_mov_b32_e32 v17, 0
	v_mov_b32_e32 v16, 0
	s_and_saveexec_b64 s[14:15], vcc
	s_cbranch_execz .LBB0_508
	v_add_u32_e32 v9, 0x60, v8
	s_movk_i32 s16, 0x920
	v_mad_i64_i32 v[18:19], s[26:27], v9, s16, v[12:13]
	global_load_dword v16, v[18:19], off nt
.LBB0_508:
	s_or_b64 exec, exec, s[14:15]
	s_and_saveexec_b64 s[14:15], vcc
	s_cbranch_execz .LBB0_510
	v_add_u32_e32 v9, 0x68, v8
	s_movk_i32 s16, 0x920
	v_mad_i64_i32 v[18:19], s[26:27], v9, s16, v[12:13]
	global_load_dword v17, v[18:19], off nt
.LBB0_510:
	s_or_b64 exec, exec, s[14:15]
	v_mov_b32_e32 v19, 0
	v_mov_b32_e32 v18, 0
	s_and_saveexec_b64 s[14:15], vcc
	s_cbranch_execz .LBB0_512
	v_add_u32_e32 v9, 0x70, v8
	s_movk_i32 s16, 0x920
	v_mad_i64_i32 v[26:27], s[26:27], v9, s16, v[12:13]
	global_load_dword v18, v[26:27], off nt
.LBB0_512:
	s_or_b64 exec, exec, s[14:15]
	s_and_saveexec_b64 s[14:15], vcc
	s_cbranch_execz .LBB0_514
	v_add_u32_e32 v9, 0x78, v8
	s_movk_i32 s16, 0x920
	v_mad_i64_i32 v[12:13], s[26:27], v9, s16, v[12:13]
	global_load_dword v19, v[12:13], off nt
.LBB0_514:
	s_or_b64 exec, exec, s[14:15]
	v_readlane_b32 s14, v252, 45
	v_readlane_b32 s15, v252, 46
	s_and_b64 vcc, exec, s[14:15]
	s_cbranch_vccz .LBB0_481
	v_ashrrev_i32_e32 v9, 31, v8
	v_lshl_add_u64 v[8:9], v[8:9], 2, s[4:5]
	global_load_dword v12, v[8:9], off nt
	global_load_dword v13, v[8:9], off offset:32 nt
	global_load_dword v26, v[8:9], off offset:64 nt
	global_load_dword v27, v[8:9], off offset:96 nt
	global_load_dword v28, v[8:9], off offset:128 nt
	global_load_dword v29, v[8:9], off offset:160 nt
	global_load_dword v30, v[8:9], off offset:192 nt
	global_load_dword v31, v[8:9], off offset:224 nt
	global_load_dword v32, v[8:9], off offset:256 nt
	global_load_dword v33, v[8:9], off offset:288 nt
	global_load_dword v34, v[8:9], off offset:320 nt
	global_load_dword v35, v[8:9], off offset:352 nt
	global_load_dword v36, v[8:9], off offset:384 nt
	global_load_dword v37, v[8:9], off offset:416 nt
	global_load_dword v38, v[8:9], off offset:448 nt
	global_load_dword v39, v[8:9], off offset:480 nt
	s_waitcnt vmcnt(14)
	v_pk_mul_f32 v[0:1], v[0:1], v[12:13]
	s_waitcnt vmcnt(12)
	v_pk_mul_f32 v[2:3], v[2:3], v[26:27]
	s_waitcnt vmcnt(10)
	v_pk_mul_f32 v[4:5], v[4:5], v[28:29]
	s_waitcnt vmcnt(8)
	v_pk_mul_f32 v[6:7], v[6:7], v[30:31]
	s_waitcnt vmcnt(6)
	v_pk_mul_f32 v[10:11], v[10:11], v[32:33]
	s_waitcnt vmcnt(4)
	v_pk_mul_f32 v[14:15], v[14:15], v[34:35]
	s_waitcnt vmcnt(2)
	v_pk_mul_f32 v[16:17], v[16:17], v[36:37]
	s_waitcnt vmcnt(0)
	v_pk_mul_f32 v[18:19], v[18:19], v[38:39]
	s_branch .LBB0_481

; DI void conv_job(const float* src, int ld, int K, int N, int kind, const float* gain, u16* dst, char* smem, int rank, int nwork) {
;     ...
;   for (int tile = rank; tile < tk_n * tn_n; tile += nwork) {
;     const int tk = tile % tk_n, tn = tile / tk_n;
;     const int k0 = tk * 128, n0 = tn * 64;
;     const int nn = tid & 63;
;     float cv[16];
; #pragma unroll
;     for (int i = 0; i < 16; ++i) cv[i] = conv_src(src, ld, kind, k0 + (tid >> 6) + 8 * i, n0 + nn);
;     if (gain) {
;       float gv[16];
; #pragma unroll
;       for (int i = 0; i < 16; ++i) gv[i] = gain[k0 + (tid >> 6) + 8 * i];
; #pragma unroll
;       for (int i = 0; i < 16; ++i) cv[i] *= gv[i];
;     }
.LBB0_522:
	s_lshr_b32 s19, s18, 31
	s_add_i32 s19, s18, s19
	s_ashr_i32 s19, s19, 1
	s_lshl_b32 s20, s19, 8
	s_lshl_b32 s19, s19, 6
	v_or_b32_e32 v0, s19, v18
	v_readlane_b32 s40, v252, 47
	s_sub_i32 s21, s14, s20
	v_ashrrev_i32_e32 v1, 31, v0
	v_readlane_b32 s42, v252, 49
	v_readlane_b32 s43, v252, 50
	v_add_u32_e32 v16, s21, v19
	s_movk_i32 s16, 0x4800
	s_waitcnt vmcnt(0)
	v_lshl_add_u64 v[24:25], v[0:1], 2, s[42:43]
	v_mad_i64_i32 v[0:1], s[22:23], v16, s16, v[24:25]
	global_load_dword v0, v[0:1], off nt
	v_add_u32_e32 v1, 8, v16
	v_mad_i64_i32 v[2:3], s[22:23], v1, s16, v[24:25]
	global_load_dword v1, v[2:3], off nt
	v_add_u32_e32 v2, 16, v16
	v_mad_i64_i32 v[2:3], s[22:23], v2, s16, v[24:25]
	global_load_dword v2, v[2:3], off nt
	v_add_u32_e32 v3, 24, v16
	v_mad_i64_i32 v[4:5], s[22:23], v3, s16, v[24:25]
	global_load_dword v3, v[4:5], off nt
	v_add_u32_e32 v4, 32, v16
	v_mad_i64_i32 v[4:5], s[22:23], v4, s16, v[24:25]
	global_load_dword v4, v[4:5], off nt
	v_add_u32_e32 v5, 40, v16
	v_mad_i64_i32 v[6:7], s[22:23], v5, s16, v[24:25]
	global_load_dword v5, v[6:7], off nt
	v_add_u32_e32 v6, 48, v16
	v_mad_i64_i32 v[6:7], s[22:23], v6, s16, v[24:25]
	global_load_dword v6, v[6:7], off nt
	v_add_u32_e32 v7, 56, v16
	v_mad_i64_i32 v[8:9], s[22:23], v7, s16, v[24:25]
	global_load_dword v7, v[8:9], off nt
	v_add_u32_e32 v8, 64, v16
	v_mad_i64_i32 v[8:9], s[22:23], v8, s16, v[24:25]
	global_load_dword v8, v[8:9], off nt
	v_add_u32_e32 v9, 0x48, v16
	v_mad_i64_i32 v[10:11], s[22:23], v9, s16, v[24:25]
	global_load_dword v9, v[10:11], off nt
	v_add_u32_e32 v10, 0x50, v16
	v_mad_i64_i32 v[10:11], s[22:23], v10, s16, v[24:25]
	global_load_dword v10, v[10:11], off nt
	v_add_u32_e32 v11, 0x58, v16
	v_mad_i64_i32 v[12:13], s[22:23], v11, s16, v[24:25]
	global_load_dword v11, v[12:13], off nt
	v_add_u32_e32 v12, 0x60, v16
	v_mad_i64_i32 v[12:13], s[22:23], v12, s16, v[24:25]
	global_load_dword v12, v[12:13], off nt
	v_add_u32_e32 v13, 0x68, v16
	v_mad_i64_i32 v[14:15], s[22:23], v13, s16, v[24:25]
	global_load_dword v13, v[14:15], off nt
	v_add_u32_e32 v14, 0x70, v16
	v_mad_i64_i32 v[14:15], s[22:23], v14, s16, v[24:25]
	global_load_dword v14, v[14:15], off nt
	v_add_u32_e32 v15, 0x78, v16
	v_mad_i64_i32 v[24:25], s[22:23], v15, s16, v[24:25]
	global_load_dword v15, v[24:25], off nt
	v_readlane_b32 s16, v252, 63
	v_readlane_b32 s17, v253, 0
	v_readlane_b32 s41, v252, 48
	s_andn2_b64 vcc, exec, s[16:17]
	v_readlane_b32 s44, v252, 51
	v_readlane_b32 s45, v252, 52
	v_readlane_b32 s46, v252, 53
	v_readlane_b32 s47, v252, 54
	v_readlane_b32 s48, v252, 55
	v_readlane_b32 s49, v252, 56
	v_readlane_b32 s50, v252, 57
	v_readlane_b32 s51, v252, 58
	v_readlane_b32 s52, v252, 59
	v_readlane_b32 s53, v252, 60
	v_readlane_b32 s54, v252, 61
	v_readlane_b32 s55, v252, 62
	s_cbranch_vccnz .LBB0_521
	v_ashrrev_i32_e32 v17, 31, v16
	v_lshl_add_u64 v[16:17], v[16:17], 2, s[40:41]
	global_load_dword v24, v[16:17], off nt
	global_load_dword v25, v[16:17], off offset:32 nt
	global_load_dword v26, v[16:17], off offset:64 nt
	global_load_dword v27, v[16:17], off offset:96 nt
	global_load_dword v28, v[16:17], off offset:128 nt
	global_load_dword v29, v[16:17], off offset:160 nt
	global_load_dword v30, v[16:17], off offset:192 nt
	global_load_dword v31, v[16:17], off offset:224 nt
	global_load_dword v32, v[16:17], off offset:256 nt
	global_load_dword v33, v[16:17], off offset:288 nt
	global_load_dword v34, v[16:17], off offset:320 nt
	global_load_dword v35, v[16:17], off offset:352 nt
	global_load_dword v36, v[16:17], off offset:384 nt
	global_load_dword v37, v[16:17], off offset:416 nt
	global_load_dword v38, v[16:17], off offset:448 nt
	global_load_dword v39, v[16:17], off offset:480 nt
	s_waitcnt vmcnt(14)
	v_pk_mul_f32 v[0:1], v[0:1], v[24:25]
	s_waitcnt vmcnt(12)
	v_pk_mul_f32 v[2:3], v[2:3], v[26:27]
	s_waitcnt vmcnt(10)
	v_pk_mul_f32 v[4:5], v[4:5], v[28:29]
	s_waitcnt vmcnt(8)
	v_pk_mul_f32 v[6:7], v[6:7], v[30:31]
	s_waitcnt vmcnt(6)
	v_pk_mul_f32 v[8:9], v[8:9], v[32:33]
	s_waitcnt vmcnt(4)
	v_pk_mul_f32 v[10:11], v[10:11], v[34:35]
	s_waitcnt vmcnt(2)
	v_pk_mul_f32 v[12:13], v[12:13], v[36:37]
	s_waitcnt vmcnt(0)
	v_pk_mul_f32 v[14:15], v[14:15], v[38:39]
	s_branch .LBB0_521

; DI float conv_src(const float* src, int ld, int kind, int k, int n) {
;     ...
;   int h = n >> 6, d = n & 63;
;   return ((k >> 8) == (h & 3)) ? src[((size_t)h * 256 + (k & 255)) * 64 + d] : 0.f;
; DI void conv_job(const float* src, int ld, int K, int N, int kind, const float* gain, u16* dst, char* smem, int rank, int nwork) {
;     ...
;   for (int tile = rank; tile < tk_n * tn_n; tile += nwork) {
;     const int tk = tile % tk_n, tn = tile / tk_n;
;     const int k0 = tk * 128, n0 = tn * 64;
;     const int nn = tid & 63;
;     float cv[16];
; #pragma unroll
;     for (int i = 0; i < 16; ++i) cv[i] = conv_src(src, ld, kind, k0 + (tid >> 6) + 8 * i, n0 + nn);
.LBB0_527:
	s_ashr_i32 s6, s21, 31
	s_lshr_b32 s6, s6, 29
	s_add_i32 s6, s21, s6
	s_ashr_i32 s6, s6, 3
	s_lshl_b32 s22, s6, 10
	s_sub_i32 s7, s18, s22
	v_add_u32_e32 v11, s7, v4
	s_ashr_i32 s7, s6, 31
	s_and_b32 s23, s6, 3
	s_lshl_b64 s[14:15], s[6:7], 16
	v_ashrrev_i32_e32 v9, 8, v11
	v_lshl_add_u64 v[2:3], v[0:1], 0, s[14:15]
	v_cmp_eq_u32_e32 vcc, s23, v9
	v_mov_b32_e32 v10, 0
	v_mov_b32_e32 v9, 0
	s_and_saveexec_b64 s[14:15], vcc
	s_cbranch_execz .LBB0_529
	v_and_b32_e32 v9, 0x3fc0, v8
	s_waitcnt vmcnt(18)
	v_lshlrev_b32_e32 v12, 2, v9
	v_mov_b32_e32 v13, v165
	v_lshl_add_u64 v[12:13], v[2:3], 0, v[12:13]
	global_load_dword v9, v[12:13], off nt
.LBB0_529:
	s_or_b64 exec, exec, s[14:15]
	s_waitcnt vmcnt(18)
	v_add_u32_e32 v12, 8, v11
	v_ashrrev_i32_e32 v12, 8, v12
	v_cmp_eq_u32_e32 vcc, s23, v12
	s_and_saveexec_b64 s[14:15], vcc
	s_cbranch_execz .LBB0_531
	v_add_u32_e32 v10, 0x200, v8
	v_and_b32_e32 v10, 0x3fc0, v10
	v_lshlrev_b32_e32 v12, 2, v10
	v_mov_b32_e32 v13, v165
	v_lshl_add_u64 v[12:13], v[2:3], 0, v[12:13]
	global_load_dword v10, v[12:13], off nt
.LBB0_531:
	s_or_b64 exec, exec, s[14:15]
	v_add_u32_e32 v12, 16, v11
	v_ashrrev_i32_e32 v12, 8, v12
	v_cmp_eq_u32_e32 vcc, s23, v12
	v_mov_b32_e32 v12, 0
	v_mov_b32_e32 v13, 0
	s_and_saveexec_b64 s[14:15], vcc
	s_cbranch_execz .LBB0_533
	v_add_u32_e32 v13, 0x400, v8
	v_and_b32_e32 v13, 0x3fc0, v13
	v_lshlrev_b32_e32 v14, 2, v13
	v_mov_b32_e32 v15, v165
	v_lshl_add_u64 v[14:15], v[2:3], 0, v[14:15]
	global_load_dword v13, v[14:15], off nt
.LBB0_533:
	s_or_b64 exec, exec, s[14:15]
	v_add_u32_e32 v14, 24, v11
	v_ashrrev_i32_e32 v14, 8, v14
	v_cmp_eq_u32_e32 vcc, s23, v14
	s_and_saveexec_b64 s[14:15], vcc
	s_cbranch_execz .LBB0_535
	v_add_u32_e32 v12, 0x600, v8
	v_and_b32_e32 v12, 0x3fc0, v12
	v_lshlrev_b32_e32 v14, 2, v12
	v_mov_b32_e32 v15, v165
	v_lshl_add_u64 v[14:15], v[2:3], 0, v[14:15]
	global_load_dword v12, v[14:15], off nt
.LBB0_535:
	s_or_b64 exec, exec, s[14:15]
	v_add_u32_e32 v14, 32, v11
	v_ashrrev_i32_e32 v14, 8, v14
	v_cmp_eq_u32_e32 vcc, s23, v14
	v_mov_b32_e32 v14, 0
	v_mov_b32_e32 v15, 0
	s_and_saveexec_b64 s[14:15], vcc
	s_cbranch_execz .LBB0_537
	v_add_u32_e32 v15, 0x800, v8
	v_and_b32_e32 v15, 0x3fc0, v15
	s_waitcnt vmcnt(17)
	v_lshlrev_b32_e32 v16, 2, v15
	v_mov_b32_e32 v17, v165
	v_lshl_add_u64 v[16:17], v[2:3], 0, v[16:17]
	global_load_dword v15, v[16:17], off nt
.LBB0_537:
	s_or_b64 exec, exec, s[14:15]
	s_waitcnt vmcnt(17)
	v_add_u32_e32 v16, 40, v11
	v_ashrrev_i32_e32 v16, 8, v16
	v_cmp_eq_u32_e32 vcc, s23, v16
	s_and_saveexec_b64 s[14:15], vcc
	s_cbranch_execz .LBB0_539
	v_add_u32_e32 v14, 0xa00, v8
	v_and_b32_e32 v14, 0x3fc0, v14
	v_lshlrev_b32_e32 v16, 2, v14
	v_mov_b32_e32 v17, v165
	v_lshl_add_u64 v[16:17], v[2:3], 0, v[16:17]
	global_load_dword v14, v[16:17], off nt
.LBB0_539:
	s_or_b64 exec, exec, s[14:15]
	v_add_u32_e32 v16, 48, v11
	v_ashrrev_i32_e32 v16, 8, v16
	v_cmp_eq_u32_e32 vcc, s23, v16
	v_mov_b32_e32 v16, 0
	v_mov_b32_e32 v17, 0
	s_and_saveexec_b64 s[14:15], vcc
	s_cbranch_execz .LBB0_541
	v_add_u32_e32 v17, 0xc00, v8
	v_and_b32_e32 v17, 0x3fc0, v17
	v_lshlrev_b32_e32 v18, 2, v17
	v_mov_b32_e32 v19, v165
	v_lshl_add_u64 v[18:19], v[2:3], 0, v[18:19]
	global_load_dword v17, v[18:19], off nt
.LBB0_541:
	s_or_b64 exec, exec, s[14:15]
	v_add_u32_e32 v18, 56, v11
	v_ashrrev_i32_e32 v18, 8, v18
	v_cmp_eq_u32_e32 vcc, s23, v18
	s_and_saveexec_b64 s[14:15], vcc
	s_cbranch_execz .LBB0_543
	v_add_u32_e32 v16, 0xe00, v8
	v_and_b32_e32 v16, 0x3fc0, v16
	v_lshlrev_b32_e32 v18, 2, v16
	v_mov_b32_e32 v19, v165
	v_lshl_add_u64 v[18:19], v[2:3], 0, v[18:19]
	global_load_dword v16, v[18:19], off nt
; DI float conv_src(const float* src, int ld, int kind, int k, int n) {
;     ...
;   int h = n >> 6, d = n & 63;
;   return ((k >> 8) == (h & 3)) ? src[((size_t)h * 256 + (k & 255)) * 64 + d] : 0.f;
; DI void conv_job(const float* src, int ld, int K, int N, int kind, const float* gain, u16* dst, char* smem, int rank, int nwork) {
;     ...
;   for (int tile = rank; tile < tk_n * tn_n; tile += nwork) {
;     const int tk = tile % tk_n, tn = tile / tk_n;
;     const int k0 = tk * 128, n0 = tn * 64;
;     const int nn = tid & 63;
;     float cv[16];
; #pragma unroll
;     for (int i = 0; i < 16; ++i) cv[i] = conv_src(src, ld, kind, k0 + (tid >> 6) + 8 * i, n0 + nn);
.LBB0_543:
	s_or_b64 exec, exec, s[14:15]
	v_add_u32_e32 v18, 64, v11
	v_ashrrev_i32_e32 v18, 8, v18
	v_cmp_eq_u32_e32 vcc, s23, v18
	v_mov_b32_e32 v18, 0
	v_mov_b32_e32 v19, 0
	s_and_saveexec_b64 s[14:15], vcc
	s_cbranch_execz .LBB0_545
	v_add_u32_e32 v19, 0x1000, v8
	v_and_b32_e32 v19, 0x3fc0, v19
	s_waitcnt vmcnt(16)
	v_lshlrev_b32_e32 v20, 2, v19
	v_mov_b32_e32 v21, v165
	v_lshl_add_u64 v[20:21], v[2:3], 0, v[20:21]
	global_load_dword v19, v[20:21], off nt
.LBB0_545:
	s_or_b64 exec, exec, s[14:15]
	s_waitcnt vmcnt(16)
	v_add_u32_e32 v20, 0x48, v11
	v_ashrrev_i32_e32 v20, 8, v20
	v_cmp_eq_u32_e32 vcc, s23, v20
	s_and_saveexec_b64 s[14:15], vcc
	s_cbranch_execz .LBB0_547
	v_add_u32_e32 v18, 0x1200, v8
	v_and_b32_e32 v18, 0x3fc0, v18
	v_lshlrev_b32_e32 v20, 2, v18
	v_mov_b32_e32 v21, v165
	v_lshl_add_u64 v[20:21], v[2:3], 0, v[20:21]
	global_load_dword v18, v[20:21], off nt
.LBB0_547:
	s_or_b64 exec, exec, s[14:15]
	v_add_u32_e32 v20, 0x50, v11
	v_ashrrev_i32_e32 v20, 8, v20
	v_cmp_eq_u32_e32 vcc, s23, v20
	v_mov_b32_e32 v20, 0
	v_mov_b32_e32 v21, 0
	s_and_saveexec_b64 s[14:15], vcc
	s_cbranch_execz .LBB0_549
	v_add_u32_e32 v21, 0x1400, v8
	v_and_b32_e32 v21, 0x3fc0, v21
	v_lshlrev_b32_e32 v22, 2, v21
	v_mov_b32_e32 v23, v165
	v_lshl_add_u64 v[22:23], v[2:3], 0, v[22:23]
	global_load_dword v21, v[22:23], off nt
.LBB0_549:
	s_or_b64 exec, exec, s[14:15]
	v_add_u32_e32 v22, 0x58, v11
	v_ashrrev_i32_e32 v22, 8, v22
	v_cmp_eq_u32_e32 vcc, s23, v22
	s_and_saveexec_b64 s[14:15], vcc
	s_cbranch_execz .LBB0_551
	v_add_u32_e32 v20, 0x1600, v8
	v_and_b32_e32 v20, 0x3fc0, v20
	v_lshlrev_b32_e32 v22, 2, v20
	v_mov_b32_e32 v23, v165
	v_lshl_add_u64 v[22:23], v[2:3], 0, v[22:23]
	global_load_dword v20, v[22:23], off nt
.LBB0_551:
	s_or_b64 exec, exec, s[14:15]
	v_add_u32_e32 v22, 0x60, v11
	v_ashrrev_i32_e32 v22, 8, v22
	v_cmp_eq_u32_e32 vcc, s23, v22
	v_mov_b32_e32 v22, 0
	v_mov_b32_e32 v23, 0
	s_and_saveexec_b64 s[14:15], vcc
	s_cbranch_execz .LBB0_553
	v_add_u32_e32 v23, 0x1800, v8
	v_and_b32_e32 v23, 0x3fc0, v23
	s_waitcnt vmcnt(0)
	v_lshlrev_b32_e32 v24, 2, v23
	v_mov_b32_e32 v25, v165
	v_lshl_add_u64 v[24:25], v[2:3], 0, v[24:25]
	global_load_dword v23, v[24:25], off nt
.LBB0_553:
	s_or_b64 exec, exec, s[14:15]
	s_waitcnt vmcnt(0)
	v_add_u32_e32 v24, 0x68, v11
	v_ashrrev_i32_e32 v24, 8, v24
	v_cmp_eq_u32_e32 vcc, s23, v24
	s_and_saveexec_b64 s[14:15], vcc
	s_cbranch_execz .LBB0_555
	v_add_u32_e32 v22, 0x1a00, v8
	v_and_b32_e32 v22, 0x3fc0, v22
	v_lshlrev_b32_e32 v24, 2, v22
	v_mov_b32_e32 v25, v165
	v_lshl_add_u64 v[24:25], v[2:3], 0, v[24:25]
	global_load_dword v22, v[24:25], off nt
.LBB0_555:
	s_or_b64 exec, exec, s[14:15]
	v_add_u32_e32 v24, 0x70, v11
	v_ashrrev_i32_e32 v24, 8, v24
	v_cmp_eq_u32_e32 vcc, s23, v24
	v_mov_b32_e32 v24, 0
	v_mov_b32_e32 v25, 0
	s_and_saveexec_b64 s[14:15], vcc
	s_cbranch_execz .LBB0_557
	v_add_u32_e32 v25, 0x1c00, v8
	v_and_b32_e32 v25, 0x3fc0, v25
	v_lshlrev_b32_e32 v26, 2, v25
	v_mov_b32_e32 v27, v165
	v_lshl_add_u64 v[26:27], v[2:3], 0, v[26:27]
	global_load_dword v25, v[26:27], off nt
.LBB0_557:
	s_or_b64 exec, exec, s[14:15]
	v_add_u32_e32 v11, 0x78, v11
	v_ashrrev_i32_e32 v11, 8, v11
	v_cmp_eq_u32_e32 vcc, s23, v11
	s_and_saveexec_b64 s[14:15], vcc
	s_cbranch_execz .LBB0_526
	v_add_u32_e32 v11, 0x1e00, v8
	v_and_b32_e32 v11, 0x3fc0, v11
	v_lshlrev_b32_e32 v26, 2, v11
	v_mov_b32_e32 v27, v165
	v_lshl_add_u64 v[2:3], v[2:3], 0, v[26:27]
	global_load_dword v24, v[2:3], off nt
	s_branch .LBB0_526

; DI void conv_job(const float* src, int ld, int K, int N, int kind, const float* gain, u16* dst, char* smem, int rank, int nwork) {
;     ...
;   for (int tile = rank; tile < tk_n * tn_n; tile += nwork) {
;     const int tk = tile % tk_n, tn = tile / tk_n;
;     const int k0 = tk * 128, n0 = tn * 64;
;     const int nn = tid & 63;
;     float cv[16];
; #pragma unroll
;     for (int i = 0; i < 16; ++i) cv[i] = conv_src(src, ld, kind, k0 + (tid >> 6) + 8 * i, n0 + nn);
;     if (gain) {
;       float gv[16];
; #pragma unroll
;       for (int i = 0; i < 16; ++i) gv[i] = gain[k0 + (tid >> 6) + 8 * i];
; #pragma unroll
;       for (int i = 0; i < 16; ++i) cv[i] *= gv[i];
;     }
.LBB0_565:
	s_ashr_i32 s8, s7, 31
	s_lshr_b32 s8, s8, 29
	s_add_i32 s8, s7, s8
	s_ashr_i32 s8, s8, 3
	s_lshl_b32 s9, s8, 10
	s_lshl_b32 s8, s8, 6
	v_or_b32_e32 v0, s8, v18
	v_readlane_b32 s40, v252, 47
	s_sub_i32 s14, s2, s9
	v_ashrrev_i32_e32 v1, 31, v0
	v_readlane_b32 s48, v252, 55
	v_readlane_b32 s49, v252, 56
	v_add_u32_e32 v16, s14, v19
	s_movk_i32 s16, 0x1400
	s_waitcnt vmcnt(0)
	v_lshl_add_u64 v[24:25], v[0:1], 2, s[48:49]
	v_mad_i64_i32 v[0:1], s[14:15], v16, s16, v[24:25]
	global_load_dword v0, v[0:1], off nt
	v_add_u32_e32 v1, 8, v16
	v_mad_i64_i32 v[2:3], s[14:15], v1, s16, v[24:25]
	global_load_dword v1, v[2:3], off nt
	v_add_u32_e32 v2, 16, v16
	v_mad_i64_i32 v[2:3], s[14:15], v2, s16, v[24:25]
	global_load_dword v2, v[2:3], off nt
	v_add_u32_e32 v3, 24, v16
	v_mad_i64_i32 v[4:5], s[14:15], v3, s16, v[24:25]
	global_load_dword v3, v[4:5], off nt
	v_add_u32_e32 v4, 32, v16
	v_mad_i64_i32 v[4:5], s[14:15], v4, s16, v[24:25]
	global_load_dword v4, v[4:5], off nt
	v_add_u32_e32 v5, 40, v16
	v_mad_i64_i32 v[6:7], s[14:15], v5, s16, v[24:25]
	global_load_dword v5, v[6:7], off nt
	v_add_u32_e32 v6, 48, v16
	v_mad_i64_i32 v[6:7], s[14:15], v6, s16, v[24:25]
	global_load_dword v6, v[6:7], off nt
	v_add_u32_e32 v7, 56, v16
	v_mad_i64_i32 v[8:9], s[14:15], v7, s16, v[24:25]
	global_load_dword v7, v[8:9], off nt
	v_add_u32_e32 v8, 64, v16
	v_mad_i64_i32 v[8:9], s[14:15], v8, s16, v[24:25]
	global_load_dword v8, v[8:9], off nt
	v_add_u32_e32 v9, 0x48, v16
	v_mad_i64_i32 v[10:11], s[14:15], v9, s16, v[24:25]
	global_load_dword v9, v[10:11], off nt
	v_add_u32_e32 v10, 0x50, v16
	v_mad_i64_i32 v[10:11], s[14:15], v10, s16, v[24:25]
	global_load_dword v10, v[10:11], off nt
	v_add_u32_e32 v11, 0x58, v16
	v_mad_i64_i32 v[12:13], s[14:15], v11, s16, v[24:25]
	global_load_dword v11, v[12:13], off nt
	v_add_u32_e32 v12, 0x60, v16
	v_mad_i64_i32 v[12:13], s[14:15], v12, s16, v[24:25]
	global_load_dword v12, v[12:13], off nt
	v_add_u32_e32 v13, 0x68, v16
	v_mad_i64_i32 v[14:15], s[14:15], v13, s16, v[24:25]
	global_load_dword v13, v[14:15], off nt
	v_add_u32_e32 v14, 0x70, v16
	v_mad_i64_i32 v[14:15], s[14:15], v14, s16, v[24:25]
	global_load_dword v14, v[14:15], off nt
	v_add_u32_e32 v15, 0x78, v16
	v_mad_i64_i32 v[24:25], s[14:15], v15, s16, v[24:25]
	global_load_dword v15, v[24:25], off nt
	v_readlane_b32 s14, v252, 45
	v_readlane_b32 s15, v252, 46
	s_andn2_b64 vcc, exec, s[14:15]
	v_readlane_b32 s41, v252, 48
	v_readlane_b32 s42, v252, 49
	v_readlane_b32 s43, v252, 50
	v_readlane_b32 s44, v252, 51
	v_readlane_b32 s45, v252, 52
	v_readlane_b32 s46, v252, 53
	v_readlane_b32 s47, v252, 54
	v_readlane_b32 s50, v252, 57
	v_readlane_b32 s51, v252, 58
	v_readlane_b32 s52, v252, 59
	v_readlane_b32 s53, v252, 60
	v_readlane_b32 s54, v252, 61
	v_readlane_b32 s55, v252, 62
	s_cbranch_vccnz .LBB0_564
	v_ashrrev_i32_e32 v17, 31, v16
	v_lshl_add_u64 v[16:17], v[16:17], 2, s[4:5]
	global_load_dword v24, v[16:17], off nt
	global_load_dword v25, v[16:17], off offset:32 nt
	global_load_dword v26, v[16:17], off offset:64 nt
	global_load_dword v27, v[16:17], off offset:96 nt
	global_load_dword v28, v[16:17], off offset:128 nt
	global_load_dword v29, v[16:17], off offset:160 nt
	global_load_dword v30, v[16:17], off offset:192 nt
	global_load_dword v31, v[16:17], off offset:224 nt
	global_load_dword v32, v[16:17], off offset:256 nt
	global_load_dword v33, v[16:17], off offset:288 nt
	global_load_dword v34, v[16:17], off offset:320 nt
	global_load_dword v35, v[16:17], off offset:352 nt
	global_load_dword v36, v[16:17], off offset:384 nt
	global_load_dword v37, v[16:17], off offset:416 nt
	global_load_dword v38, v[16:17], off offset:448 nt
	global_load_dword v39, v[16:17], off offset:480 nt
	s_waitcnt vmcnt(14)
	v_pk_mul_f32 v[0:1], v[0:1], v[24:25]
	s_waitcnt vmcnt(12)
	v_pk_mul_f32 v[2:3], v[2:3], v[26:27]
	s_waitcnt vmcnt(10)
	v_pk_mul_f32 v[4:5], v[4:5], v[28:29]
	s_waitcnt vmcnt(8)
	v_pk_mul_f32 v[6:7], v[6:7], v[30:31]
	s_waitcnt vmcnt(6)
	v_pk_mul_f32 v[8:9], v[8:9], v[32:33]
	s_waitcnt vmcnt(4)
	v_pk_mul_f32 v[10:11], v[10:11], v[34:35]
	s_waitcnt vmcnt(2)
	v_pk_mul_f32 v[12:13], v[12:13], v[36:37]
	s_waitcnt vmcnt(0)
	v_pk_mul_f32 v[14:15], v[14:15], v[38:39]
	s_branch .LBB0_564

; DI void conv_job(const float* src, int ld, int K, int N, int kind, const float* gain, u16* dst, char* smem, int rank, int nwork) {
;     ...
;   for (int tile = rank; tile < tk_n * tn_n; tile += nwork) {
;     const int tk = tile % tk_n, tn = tile / tk_n;
;     const int k0 = tk * 128, n0 = tn * 64;
;     const int nn = tid & 63;
;     float cv[16];
; #pragma unroll
;     for (int i = 0; i < 16; ++i) cv[i] = conv_src(src, ld, kind, k0 + (tid >> 6) + 8 * i, n0 + nn);
;     if (gain) {
;       float gv[16];
; #pragma unroll
;       for (int i = 0; i < 16; ++i) gv[i] = gain[k0 + (tid >> 6) + 8 * i];
; #pragma unroll
;       for (int i = 0; i < 16; ++i) cv[i] *= gv[i];
;     }
.LBB0_571:
	s_ashr_i32 s8, s0, 31
	s_lshr_b32 s8, s8, 29
	s_add_i32 s8, s0, s8
	s_ashr_i32 s8, s8, 3
	s_lshl_b32 s9, s8, 10
	s_lshl_b32 s8, s8, 6
	v_or_b32_e32 v0, s8, v18
	s_sub_i32 s14, s1, s9
	v_ashrrev_i32_e32 v1, 31, v0
	v_add_u32_e32 v16, s14, v19
	s_waitcnt vmcnt(0)
	v_lshl_add_u64 v[24:25], v[0:1], 2, s[6:7]
	s_movk_i32 s16, 0x3000
	v_mad_i64_i32 v[0:1], s[14:15], v16, s16, v[24:25]
	global_load_dword v0, v[0:1], off nt
	v_add_u32_e32 v1, 8, v16
	v_mad_i64_i32 v[2:3], s[14:15], v1, s16, v[24:25]
	global_load_dword v1, v[2:3], off nt
	v_add_u32_e32 v2, 16, v16
	v_mad_i64_i32 v[2:3], s[14:15], v2, s16, v[24:25]
	global_load_dword v2, v[2:3], off nt
	v_add_u32_e32 v3, 24, v16
	v_mad_i64_i32 v[4:5], s[14:15], v3, s16, v[24:25]
	global_load_dword v3, v[4:5], off nt
	v_add_u32_e32 v4, 32, v16
	v_mad_i64_i32 v[4:5], s[14:15], v4, s16, v[24:25]
	global_load_dword v4, v[4:5], off nt
	v_add_u32_e32 v5, 40, v16
	v_mad_i64_i32 v[6:7], s[14:15], v5, s16, v[24:25]
	global_load_dword v5, v[6:7], off nt
	v_add_u32_e32 v6, 48, v16
	v_mad_i64_i32 v[6:7], s[14:15], v6, s16, v[24:25]
	global_load_dword v6, v[6:7], off nt
	v_add_u32_e32 v7, 56, v16
	v_mad_i64_i32 v[8:9], s[14:15], v7, s16, v[24:25]
	global_load_dword v7, v[8:9], off nt
	v_add_u32_e32 v8, 64, v16
	v_mad_i64_i32 v[8:9], s[14:15], v8, s16, v[24:25]
	global_load_dword v8, v[8:9], off nt
	v_add_u32_e32 v9, 0x48, v16
	v_mad_i64_i32 v[10:11], s[14:15], v9, s16, v[24:25]
	global_load_dword v9, v[10:11], off nt
	v_add_u32_e32 v10, 0x50, v16
	v_mad_i64_i32 v[10:11], s[14:15], v10, s16, v[24:25]
	global_load_dword v10, v[10:11], off nt
	v_add_u32_e32 v11, 0x58, v16
	v_mad_i64_i32 v[12:13], s[14:15], v11, s16, v[24:25]
	global_load_dword v11, v[12:13], off nt
	v_add_u32_e32 v12, 0x60, v16
	v_mad_i64_i32 v[12:13], s[14:15], v12, s16, v[24:25]
	global_load_dword v12, v[12:13], off nt
	v_add_u32_e32 v13, 0x68, v16
	v_mad_i64_i32 v[14:15], s[14:15], v13, s16, v[24:25]
	global_load_dword v13, v[14:15], off nt
	v_add_u32_e32 v14, 0x70, v16
	v_mad_i64_i32 v[14:15], s[14:15], v14, s16, v[24:25]
	global_load_dword v14, v[14:15], off nt
	v_add_u32_e32 v15, 0x78, v16
	v_mad_i64_i32 v[24:25], s[14:15], v15, s16, v[24:25]
	global_load_dword v15, v[24:25], off nt
	v_readlane_b32 s14, v252, 45
	v_readlane_b32 s15, v252, 46
	s_andn2_b64 vcc, exec, s[14:15]
	s_cbranch_vccnz .LBB0_570
	v_ashrrev_i32_e32 v17, 31, v16
	v_lshl_add_u64 v[16:17], v[16:17], 2, s[4:5]
	global_load_dword v24, v[16:17], off nt
	global_load_dword v25, v[16:17], off offset:32 nt
	global_load_dword v26, v[16:17], off offset:64 nt
	global_load_dword v27, v[16:17], off offset:96 nt
	global_load_dword v28, v[16:17], off offset:128 nt
	global_load_dword v29, v[16:17], off offset:160 nt
	global_load_dword v30, v[16:17], off offset:192 nt
	global_load_dword v31, v[16:17], off offset:224 nt
	global_load_dword v32, v[16:17], off offset:256 nt
	global_load_dword v33, v[16:17], off offset:288 nt
	global_load_dword v34, v[16:17], off offset:320 nt
	global_load_dword v35, v[16:17], off offset:352 nt
	global_load_dword v36, v[16:17], off offset:384 nt
	global_load_dword v37, v[16:17], off offset:416 nt
	global_load_dword v38, v[16:17], off offset:448 nt
	global_load_dword v39, v[16:17], off offset:480 nt
	s_waitcnt vmcnt(14)
	v_pk_mul_f32 v[0:1], v[0:1], v[24:25]
	s_waitcnt vmcnt(12)
	v_pk_mul_f32 v[2:3], v[2:3], v[26:27]
	s_waitcnt vmcnt(10)
	v_pk_mul_f32 v[4:5], v[4:5], v[28:29]
	s_waitcnt vmcnt(8)
	v_pk_mul_f32 v[6:7], v[6:7], v[30:31]
	s_waitcnt vmcnt(6)
	v_pk_mul_f32 v[8:9], v[8:9], v[32:33]
	s_waitcnt vmcnt(4)
	v_pk_mul_f32 v[10:11], v[10:11], v[34:35]
	s_waitcnt vmcnt(2)
	v_pk_mul_f32 v[12:13], v[12:13], v[36:37]
	s_waitcnt vmcnt(0)
	v_pk_mul_f32 v[14:15], v[14:15], v[38:39]
	s_branch .LBB0_570
